# GEMM-side workgroups of P2 do not wait for the P1-P2 grid barrier (they read nothing P1 wrote; they still post their arrival), so their tiles start earlier; SWA units moved off the recurrence workgrou
# speedup vs baseline: 1.0205x; 1.0150x over previous
; __device__ __forceinline__ unsigned xb_ld(unsigned* p)              { return __hip_atomic_load(p, __ATOMIC_RELAXED, __HIP_MEMORY_SCOPE_AGENT); }
; __device__ __forceinline__ unsigned xb_add(unsigned* p, unsigned v) { return __hip_atomic_fetch_add(p, v, __ATOMIC_RELAXED, __HIP_MEMORY_SCOPE_AGENT); }
; #define XB_SPIN(cond, bar) do { unsigned _sp = 0; while (cond) { __builtin_amdgcn_s_sleep(1); \
;     if ((++_sp & 255u) == 0u) { if (xb_ld(&(bar)[XB_TMO])) break; if (_sp > XB_SPIN_CAP) { atomicAdd(&(bar)[XB_TMO], 1u); break; } } } } while (0)
; __device__ __forceinline__ void xcd_barrier(const XcdBarrier& b) {
;     asm volatile("s_waitcnt vmcnt(0)" ::: "memory");
;     __syncthreads();
;     if (threadIdx.x == 0) {
;         unsigned* bar = b.bar;
;         __builtin_amdgcn_s_waitcnt(0);
;         unsigned nloc = b.st[0], nx = b.st[1];
;         if (nloc == 0u) { xcd_barrier_complete(bar, b.x, nloc, nx); b.st[0] = nloc; b.st[1] = nx; }
;         const unsigned old = xb_add(&bar[XB_XSUB(b.x)], 1u);
;         const unsigned gen = old / nloc;
;         if (old + 1u == (gen + 1u) * nloc) {
;             __builtin_amdgcn_fence(__ATOMIC_RELEASE, "agent");
;             asm volatile("s_waitcnt vmcnt(0)" ::: "memory");
;             const unsigned og = xb_add(&bar[XB_TOP], 1u);
;             const unsigned tg = og / nx;
;             if (og + 1u == (tg + 1u) * nx) xb_add(&bar[XB_TOPGEN], 1u);
;             else XB_SPIN(xb_ld(&bar[XB_TOPGEN]) == tg, bar);
;             __builtin_amdgcn_fence(__ATOMIC_ACQUIRE, "agent");
;             xb_add(&bar[XB_XGEN(b.x)], 1u);
;             asm volatile("s_waitcnt vmcnt(0)" ::: "memory");
;         } else {
;             XB_SPIN(xb_ld(&bar[XB_XGEN(b.x)]) == gen, bar);
;             __builtin_amdgcn_fence(__ATOMIC_ACQUIRE, "agent");
;             asm volatile("s_waitcnt vmcnt(0)" ::: "memory");
;         }
.LBB0_223:
	s_or_b64 exec, exec, s[14:15]
	v_cvt_f32_u32_e32 v4, v2
	s_waitcnt vmcnt(0)
	v_readfirstlane_b32 s8, v3
	v_sub_u32_e32 v3, 0, v2
	v_rcp_iflag_f32_e32 v4, v4
	v_add_u32_e32 v5, s8, v1
	v_mul_f32_e32 v4, 0x4f7ffffe, v4
	v_cvt_u32_f32_e32 v4, v4
	v_mul_lo_u32 v1, v3, v4
	v_mul_hi_u32 v1, v4, v1
	v_add_u32_e32 v1, v4, v1
	v_mul_hi_u32 v1, v5, v1
	v_mul_lo_u32 v3, v1, v2
	v_sub_u32_e32 v3, v5, v3
	v_add_u32_e32 v4, 1, v1
	v_cmp_ge_u32_e32 vcc, v3, v2
	s_nop 1
	v_cndmask_b32_e32 v1, v1, v4, vcc
	v_sub_u32_e32 v4, v3, v2
	v_cndmask_b32_e32 v3, v3, v4, vcc
	v_add_u32_e32 v4, 1, v1
	v_cmp_ge_u32_e32 vcc, v3, v2
	v_add_u32_e32 v3, 1, v5
	s_nop 0
	v_cndmask_b32_e32 v1, v1, v4, vcc
	v_mul_lo_u32 v4, v2, v1
	v_add_u32_e32 v2, v4, v2
	v_cmp_ne_u32_e32 vcc, v3, v2
	s_and_saveexec_b64 s[8:9], vcc
	s_xor_b64 s[12:13], exec, s[8:9]
	s_cbranch_execz .LBB0_237
	s_cmpk_eq_i32 s33, 0x100
	s_cbranch_scc0 .Ls1_wait
	s_cmp_gt_i32 s2, 63
	s_cbranch_scc1 .LBB0_237
.Ls1_wait:
	s_waitcnt lgkmcnt(0)
	v_mov_b32_e32 v0, 0x2000
	global_load_dword v0, v0, s[10:11] offset:1024 sc1
	s_add_u32 s18, s10, 0x2400
	s_addc_u32 s19, s11, 0
	s_waitcnt vmcnt(0)
	v_cmp_eq_u32_e32 vcc, v0, v1
	s_and_saveexec_b64 s[14:15], vcc
	s_cbranch_execz .LBB0_236
	s_add_u32 s16, s92, 0x4200
	s_addc_u32 s17, s93, 0
	s_mov_b32 s8, 1
	s_mov_b64 s[20:21], 0
	v_mov_b32_e32 v0, 0
	s_branch .LBB0_227

; __device__ __forceinline__ void swa_units(Frame& F, int u0, int stride) {
;     if (u0 >= 512) return;
;     u32x4 kt_[4], vt_[4];
;     __syncthreads();
;     swa_load(F, u0, kt_, vt_);
;     swa_stage(F, kt_, vt_);
;     __syncthreads();
;     for (int u = u0;;) {
;         const int un = u + stride; const bool has = un < 512;
.LBB0_583:
	s_mov_b32 s101, s2
	s_mov_b32 s100, s33
	s_movk_i32 s99, 0x200
	s_cmpk_eq_i32 s33, 0x100
	s_cbranch_scc0 .Lswa_cfg
	s_movk_i32 s100, 0x80
	s_cmp_gt_i32 s2, 0x7f
	s_cbranch_scc1 .Lswa_cfg
	s_movk_i32 s99, 0x80
	s_movk_i32 s100, 64
	s_add_i32 s101, s2, 0xffffffc0
	s_cmp_gt_i32 s2, 63
	s_cbranch_scc1 .Lswa_cfg
	s_movk_i32 s101, 0x200
